# GQA loop: LDS-DMA issue alternates between wave halves per iteration (duty wave issues its own and its SIMD partner's pieces)
# baseline (speedup 1.0000x reference)
; template <int NCB, bool DIFF, bool STAT>
; __device__ __forceinline__ void attn_unit(LAS char* lds, const Params& P, int s, int head, int qb, float sref) {
;     ...
;     for (int mp = 0; mp < NMAP; ++mp) {
;         const bf16* Qw; const unsigned char* Kimg; const unsigned char* Vimg;
;         if constexpr (DIFF) {
;             Qw = (const bf16*)(ws + WS_QD) + ((size_t)sb * 8 + (size_t)(head * 2 + mp) * n + qw) * 64;
;             Kimg = ws + WS_KD + ((size_t)sb * 8 + (size_t)(head * 2 + mp) * n) * 128;
;             Vimg = ws + WS_VD + ((size_t)sb * 4 + (size_t)head * n) * 256;
;         } else {
;             Qw = (const bf16*)(ws + WS_QG) + ((size_t)sb * 8 + (size_t)head * n + qw) * 64;
;             Kimg = ws + WS_KG + ((size_t)sb * 2 + (size_t)(head >> 2) * n) * 128;
;             Vimg = ws + WS_VG + ((size_t)sb * 2 + (size_t)(head >> 2) * n) * 128;
;         }
;         const unsigned dvoff = (unsigned)(wid * 1024 + lane * 16);
;         const unsigned kdst = lds0 + L_K + wid * 1024, vdst = lds0 + L_V + wid * 1024;
;     ...
;         __syncthreads();
;         DMA(0, 0); DMA(1, 1); DMA(2, 2);
;         bf16x8 qr[4];
; #pragma unroll
;         for (int d0 = 0; d0 < 4; ++d0) qr[d0] = *(const bf16x8*)(Qw + (size_t)r32 * 64 + d0 * 16 + hi * 8);
.LBB0_588:
	v_readlane_b32 s4, v254, 45
	v_readlane_b32 s5, v254, 46
	s_lshl_b32 s8, s64, 14
	s_nop 3
	global_load_dword v1, v0, s[4:5]
	s_lshl_b32 s4, s64, 12
	s_add_i32 s9, s4, 0x6000
	s_cmp_lt_u32 s64, 2
	s_cselect_b64 s[4:5], -1, 0
	s_and_b64 s[6:7], s[4:5], exec
	s_mov_b32 s6, 0x42200000
	s_cselect_b32 s48, 0x100, 64
	s_cselect_b32 s14, s8, s9
	s_lshl_b32 s42, s63, 8
	s_waitcnt vmcnt(0)
	v_cmp_nge_f32_e32 vcc, s6, v1
	s_cbranch_vccnz .LBB0_595
	v_mov_b32_e32 v42, v230
	s_lshl_b64 s[6:7], s[14:15], 3
	v_readfirstlane_b32 s9, v42
	s_ashr_i32 s8, s9, 6
	s_lshl_b32 s43, s8, 5
	s_add_i32 s43, s43, s42
	s_and_b64 s[12:13], s[4:5], exec
	s_mov_b32 s73, s15
	s_cselect_b32 s40, 14, 12
	s_lshl_b64 s[12:13], s[72:73], s40
	s_add_u32 s6, s6, s12
	s_addc_u32 s7, s7, s13
	s_ashr_i32 s12, s43, 31
	s_add_u32 s6, s6, s43
	s_addc_u32 s7, s7, s12
	s_lshl_b64 s[6:7], s[6:7], 7
	s_add_u32 s12, s92, s6
	s_addc_u32 s13, s93, s7
	s_lshr_b32 s6, s72, 2
	s_mov_b32 s7, s15
	s_lshl_b64 s[6:7], s[6:7], s40
	s_lshl_b64 s[40:41], s[14:15], 8
	s_lshl_b64 s[6:7], s[6:7], 7
	s_add_u32 s6, s40, s6
	s_addc_u32 s7, s41, s7
	v_readlane_b32 s16, v254, 47
	s_add_u32 s40, s16, s6
	v_readlane_b32 s16, v254, 48
	s_addc_u32 s41, s16, s7
	v_readlane_b32 s16, v254, 49
	v_and_b32_e32 v133, 63, v42
	s_add_u32 s6, s16, s6
	v_readlane_b32 s16, v254, 50
	v_lshlrev_b32_e32 v43, 4, v133
	s_addc_u32 s7, s16, s7
	s_lshl_b32 s47, s8, 10
	v_or_b32_e32 v134, s47, v43
	v_xor_b32_e32 v189, 0x1000, v134
	s_lshr_b32 s100, s8, 2
	s_add_i32 s46, s47, s65
	s_add_i32 s47, s47, 0
	s_add_u32 s50, s40, 0x2000
	s_addc_u32 s51, s41, 0
	s_add_u32 s54, s6, 0x2000
	s_addc_u32 s55, s7, 0
	s_add_u32 s56, s40, 0x4000
	v_and_b32_e32 v132, 31, v42
	s_addc_u32 s57, s41, 0
	s_barrier
	s_mov_b32 s8, m0
	s_mov_b32 m0, s46
	s_nop 0
	global_load_lds_dwordx4 v134, s[40:41]
	s_mov_b32 m0, s8
	s_add_u32 s58, s6, 0x4000
	v_lshlrev_b32_e32 v2, 7, v132
	v_mov_b32_e32 v3, v0
	s_mov_b32 s8, m0
	s_mov_b32 m0, s47
	s_nop 0
	global_load_lds_dwordx4 v134, s[6:7]
	s_mov_b32 m0, s8
	s_addc_u32 s59, s7, 0
	v_lshl_add_u64 v[2:3], s[12:13], 0, v[2:3]
	s_add_i32 s8, s47, 0x16000
	s_mov_b32 s12, m0
	s_mov_b32 m0, s8
	s_nop 0
	global_load_lds_dwordx4 v134, s[50:51]
	s_mov_b32 m0, s12
	v_bfe_u32 v150, v42, 5, 1
	s_add_i32 s8, s47, 0x4000
	s_mov_b32 s12, m0
	s_mov_b32 m0, s8
	s_nop 0
	global_load_lds_dwordx4 v134, s[54:55]
	s_mov_b32 m0, s12
	v_lshlrev_b32_e32 v148, 4, v150
	v_mov_b32_e32 v149, v0
	s_add_i32 s8, s47, 0x18000
	s_mov_b32 s12, m0
	s_mov_b32 m0, s8
	s_nop 0
	global_load_lds_dwordx4 v134, s[56:57]
	s_mov_b32 m0, s12
	v_lshl_add_u64 v[6:7], v[2:3], 0, v[148:149]
	s_add_i32 s8, s47, 0x8000
	s_mov_b32 s12, m0
	s_mov_b32 m0, s8
	s_nop 0
	global_load_lds_dwordx4 v134, s[58:59]
	s_mov_b32 m0, s12
	global_load_dwordx4 v[124:127], v[6:7], off
	global_load_dwordx4 v[120:123], v[6:7], off offset:32
	global_load_dwordx4 v[116:119], v[6:7], off offset:64
	global_load_dwordx4 v[112:115], v[6:7], off offset:96
	v_mov_b32_e32 v2, v0
	v_mov_b32_e32 v3, v0
	v_mov_b32_e32 v4, v0
	v_mov_b32_e32 v5, v0
	v_mov_b32_e32 v6, v0
	v_mov_b32_e32 v7, v0
	v_mov_b32_e32 v8, v0
	v_mov_b32_e32 v9, v0
	v_mov_b32_e32 v10, v0
	v_mov_b32_e32 v11, v0
	v_mov_b32_e32 v12, v0
	v_mov_b32_e32 v13, v0
	v_mov_b32_e32 v14, v0
	v_mov_b32_e32 v15, v0
	v_mov_b32_e32 v1, v0
	v_mov_b64_e32 v[16:17], v[14:15]
	v_mov_b64_e32 v[14:15], v[12:13]
	v_mov_b64_e32 v[12:13], v[10:11]
	v_mov_b64_e32 v[10:11], v[8:9]
	v_mov_b64_e32 v[8:9], v[6:7]
	v_mov_b64_e32 v[6:7], v[4:5]
	v_mov_b64_e32 v[4:5], v[2:3]
	v_mov_b64_e32 v[2:3], v[0:1]
	v_lshlrev_b32_e32 v1, 10, v150
	v_lshlrev_b32_e32 v18, 4, v132
	v_add3_u32 v135, s65, v1, v18
	s_waitcnt vmcnt(0) lgkmcnt(0)
	s_barrier
; #define LAS __attribute__((address_space(3)))
; #define WAIT_BAR() asm volatile("s_waitcnt vmcnt(0) lgkmcnt(0)\n\ts_barrier" ::: "memory")
; #define BMODE(t) do { if constexpr (DIFF) { const int dd = (t) * 64 - qw; float cbn; if (dd <= -191) { bm = 1; cbn = bL; } else if (dd >= 159) { bm = 1; cbn = bR; } else { bm = 2; cbn = 0.f; } \
;             ix = dd - r32 + 256 + 4 * hi; if (cbn != cb) { cb = cbn; moved = true; } } } while (0)
; #define NEGM() do { if (moved) { const float v_ = cb - m_reg; _Pragma("unroll") for (int r = 0; r < 16; ++r) negm[r] = v_; asm volatile("" : "+v"(negm)); } } while (0)
; #define WAIT_BAR() asm volatile("s_waitcnt vmcnt(0) lgkmcnt(0)\n\ts_barrier" ::: "memory")
; #define MFMA32(a, b, c) __builtin_amdgcn_mfma_f32_32x32x16_bf16(a, b, c, 0, 0, 0)
; #define BMODE(t) do { if constexpr (DIFF) { const int dd = (t) * 64 - qw; float cbn; if (dd <= -191) { bm = 1; cbn = bL; } else if (dd >= 159) { bm = 1; cbn = bR; } else { bm = 2; cbn = 0.f; } \
;             ix = dd - r32 + 256 + 4 * hi; if (cbn != cb) { cb = cbn; moved = true; } } } while (0)
; #define NEGM() do { if (moved) { const float v_ = cb - m_reg; _Pragma("unroll") for (int r = 0; r < 16; ++r) negm[r] = v_; asm volatile("" : "+v"(negm)); } } while (0)
; template <int NCB, bool DIFF, bool STAT>
; __device__ __forceinline__ void attn_unit(LAS char* lds, const Params& P, int s, int head, int qb, float sref) {
;     ...
;         WAIT_BAR();
;         BMODE(0); NEGM();
;         { const LAS char* kp_ = kp0;
; #pragma unroll
;           for (int d0 = 0; d0 < 4; ++d0) { const bf16x8 b0 = *(const LAS bf16x8*)(kp_ + d0 * 2048), b1 = *(const LAS bf16x8*)(kp_ + d0 * 2048 + 512);
;               if (d0 == 0) { if constexpr (ZREF) { pA0 = MFMA32(b0, qr[0], f32x16{}); pA1 = MFMA32(b1, qr[0], f32x16{}); } else { pA0 = MFMA32(b0, qr[0], negm); pA1 = MFMA32(b1, qr[0], negm); } } else { pA0 = MFMA32(b0, qr[d0], pA0); pA1 = MFMA32(b1, qr[d0], pA1); } } }
;         bias_add<DIFF>(pA0, pA1, bm, tab, ix);
;         if constexpr (!STAT) rowmax_decide<DIFF, true>(pA0, pA1, m_reg, alA, moved, bm, tab, ix); else moved = false;
; #pragma unroll
;         for (int r = 0; r < 16; ++r) { pA0[r] = __builtin_amdgcn_exp2f(pA0[r]); pA1[r] = __builtin_amdgcn_exp2f(pA1[r]); }
;         int sl_prev = 0, sl_cur = 1;
;         bf16x8 kf[3];
	ds_read_b128 v[2:5], v135
	ds_read_b128 v[18:21], v135 offset:512
	ds_read_b128 v[34:37], v135 offset:2048
	ds_read_b128 v[38:41], v135 offset:2560
	s_add_i32 s50, s48, -1
	v_lshlrev_b32_e32 v1, 1, v42
	v_lshlrev_b32_e32 v42, 3, v133
	s_add_u32 s6, s6, 0x8000
	s_addc_u32 s7, s7, 0
	v_and_b32_e32 v1, 32, v1
	s_add_u32 s40, s40, 0x8000
	s_mov_b32 s49, 4
	s_mov_b32 s8, 1
	s_mov_b32 s54, 0
	s_addc_u32 s41, s41, 0
	s_waitcnt vmcnt(3) lgkmcnt(3)
	v_mfma_f32_32x32x16_bf16 v[2:17], v[2:5], v[124:127], 0
	s_waitcnt lgkmcnt(2)
	v_mfma_f32_32x32x16_bf16 v[18:33], v[18:21], v[124:127], 0
	s_waitcnt vmcnt(2) lgkmcnt(1)
	v_mfma_f32_32x32x16_bf16 v[2:17], v[34:37], v[120:123], v[2:17]
	s_waitcnt lgkmcnt(0)
	v_mfma_f32_32x32x16_bf16 v[18:33], v[38:41], v[120:123], v[18:33]
	ds_read_b128 v[34:37], v135 offset:4096
	ds_read_b128 v[38:41], v135 offset:4608
	s_waitcnt vmcnt(1) lgkmcnt(1)
	v_mfma_f32_32x32x16_bf16 v[2:17], v[34:37], v[116:119], v[2:17]
	ds_read_b128 v[34:37], v135 offset:6144
	s_waitcnt lgkmcnt(1)
	v_mfma_f32_32x32x16_bf16 v[18:33], v[38:41], v[116:119], v[18:33]
	ds_read_b128 v[38:41], v135 offset:6656
	s_waitcnt vmcnt(0) lgkmcnt(1)
	v_mfma_f32_32x32x16_bf16 v[2:17], v[34:37], v[112:115], v[2:17]
	v_and_b32_e32 v34, 24, v42
	v_and_b32_e32 v35, 0xc0, v43
	v_and_b32_e32 v36, 0x100, v42
	v_add3_u32 v34, 0, v34, v35
	v_add3_u32 v1, v34, v1, v36
	s_nop 6
	v_exp_f32_e32 v64, v2
	s_waitcnt lgkmcnt(0)
	v_mfma_f32_32x32x16_bf16 v[18:33], v[38:41], v[112:115], v[18:33]
	v_exp_f32_e32 v65, v3
	v_exp_f32_e32 v66, v4
	v_exp_f32_e32 v67, v5
	v_exp_f32_e32 v68, v6
	v_exp_f32_e32 v69, v7
	v_exp_f32_e32 v70, v8
	v_exp_f32_e32 v71, v9
	s_nop 4
	v_exp_f32_e32 v48, v18
	v_exp_f32_e32 v49, v19
	v_exp_f32_e32 v50, v20
	v_exp_f32_e32 v51, v21
	v_exp_f32_e32 v52, v22
	v_exp_f32_e32 v53, v23
	v_exp_f32_e32 v54, v24
	v_exp_f32_e32 v55, v25
	v_exp_f32_e32 v56, v26
	v_exp_f32_e32 v57, v27
	v_exp_f32_e32 v58, v28
	v_exp_f32_e32 v59, v29
	v_exp_f32_e32 v60, v30
	v_exp_f32_e32 v61, v31
	v_exp_f32_e32 v62, v32
	v_exp_f32_e32 v63, v33
	v_exp_f32_e32 v72, v10
	v_exp_f32_e32 v73, v11
	v_exp_f32_e32 v74, v12
	v_exp_f32_e32 v75, v13
	v_exp_f32_e32 v76, v14
	v_exp_f32_e32 v77, v15
	v_exp_f32_e32 v78, v16
	v_exp_f32_e32 v79, v17
	v_mov_b32_e32 v14, 0
	v_mov_b32_e32 v144, 0
	v_mov_b32_e32 v145, 0
	v_mov_b32_e32 v146, 0
	v_mov_b32_e32 v147, 0
	v_and_b32_e32 v140, 15, v230
	v_bfe_u32 v141, v230, 4, 1
	v_mov_b32_e32 v142, 0x3f803f80
	v_cmp_eq_u32_e64 s[98:99], v140, v141
	s_nop 1
	v_cndmask_b32_e64 v140, 0, v142, s[98:99]
	v_mov_b32_e32 v141, v140
	v_mov_b32_e32 v142, v140
	v_mov_b32_e32 v143, v140
	v_mov_b32_e32 v16, 0
	v_mov_b32_e32 v17, v14
	v_mov_b32_e32 v18, v14
	v_mov_b32_e32 v19, v14
	v_mov_b32_e32 v20, v14
	v_mov_b32_e32 v21, v14
	v_mov_b32_e32 v22, v14
	v_mov_b32_e32 v23, v14
	v_mov_b32_e32 v24, v14
	v_mov_b32_e32 v25, v14
	v_mov_b32_e32 v26, v14
	v_mov_b32_e32 v27, v14
	v_mov_b32_e32 v28, v14
	v_mov_b32_e32 v29, v14
	v_mov_b32_e32 v30, v14
	v_mov_b32_e32 v31, v14
	v_mov_b32_e32 v32, 0
	v_mov_b32_e32 v33, v14
	v_mov_b32_e32 v34, v14
	v_mov_b32_e32 v35, v14
	v_mov_b32_e32 v36, v14
	v_mov_b32_e32 v37, v14
	v_mov_b32_e32 v38, v14
	v_mov_b32_e32 v39, v14
	v_mov_b32_e32 v40, v14
	v_mov_b32_e32 v41, v14
	v_mov_b32_e32 v42, v14
	v_mov_b32_e32 v43, v14
	v_mov_b32_e32 v44, v14
	v_mov_b32_e32 v45, v14
	v_mov_b32_e32 v46, v14
	v_mov_b32_e32 v47, v14
	s_branch .LBB0_591

.LBB0_591:
	v_lshl_add_u32 v136, s8, 13, v135
	ds_read_b128 v[2:5], v136
	ds_read_b128 v[6:9], v136 offset:512
	s_lshl_b32 s12, s54, 14
	v_add_u32_e32 v15, s12, v1
	s_waitcnt lgkmcnt(1)
	v_mfma_f32_32x32x16_bf16 v[96:111], v[2:5], v[124:127], 0
	ds_read_b128 v[10:13], v136 offset:2048
	v_cvt_pk_bf16_f32 v128, v64, v65
	v_cvt_pk_bf16_f32 v129, v66, v67
	s_waitcnt lgkmcnt(1)
	v_mfma_f32_32x32x16_bf16 v[80:95], v[6:9], v[124:127], 0
	ds_read_b128 v[2:5], v136 offset:2560
	v_cvt_pk_bf16_f32 v130, v68, v69
	v_cvt_pk_bf16_f32 v131, v70, v71
	s_waitcnt lgkmcnt(1)
	v_mfma_f32_32x32x16_bf16 v[96:111], v[10:13], v[120:123], v[96:111]
	ds_read_b128 v[6:9], v136 offset:4096
	v_mfma_f32_16x16x32_bf16 v[144:147], v[128:131], v[140:143], v[144:147]
	v_cvt_pk_bf16_f32 v10, v72, v73
	v_cvt_pk_bf16_f32 v11, v74, v75
	s_waitcnt lgkmcnt(1)
	v_mfma_f32_32x32x16_bf16 v[80:95], v[2:5], v[120:123], v[80:95]
	ds_read_b128 v[64:67], v136 offset:4608
	v_cvt_pk_bf16_f32 v12, v76, v77
	v_cvt_pk_bf16_f32 v13, v78, v79
	s_waitcnt lgkmcnt(1)
	v_mfma_f32_32x32x16_bf16 v[96:111], v[6:9], v[116:119], v[96:111]
	ds_read_b128 v[2:5], v136 offset:6144
	v_mfma_f32_16x16x32_bf16 v[144:147], v[10:13], v[140:143], v[144:147]
	v_cvt_pk_bf16_f32 v6, v48, v49
	v_cvt_pk_bf16_f32 v7, v50, v51
	s_waitcnt lgkmcnt(1)
	v_mfma_f32_32x32x16_bf16 v[80:95], v[64:67], v[116:119], v[80:95]
	ds_read_b128 v[68:71], v136 offset:6656
	v_cvt_pk_bf16_f32 v8, v52, v53
	v_cvt_pk_bf16_f32 v9, v54, v55
	s_waitcnt lgkmcnt(1)
	v_mfma_f32_32x32x16_bf16 v[96:111], v[2:5], v[112:115], v[96:111]
	v_cvt_pk_bf16_f32 v2, v56, v57
	v_cvt_pk_bf16_f32 v3, v58, v59
	v_mfma_f32_16x16x32_bf16 v[144:147], v[6:9], v[140:143], v[144:147]
	ds_read_b64_tr_b16 v[48:49], v15
	ds_read_b64_tr_b16 v[50:51], v15 offset:1024
	s_waitcnt lgkmcnt(2)
	v_mfma_f32_32x32x16_bf16 v[80:95], v[68:71], v[112:115], v[80:95]
	v_cvt_pk_bf16_f32 v4, v60, v61
	v_cvt_pk_bf16_f32 v5, v62, v63
	ds_read_b64_tr_b16 v[52:53], v15 offset:512
	ds_read_b64_tr_b16 v[54:55], v15 offset:1536
	s_add_i32 s51, s49, -1
	s_lshr_b32 s56, s49, 1
	s_xor_b32 s56, s56, s100
	s_bitcmp1_b32 s56, 0
	s_cbranch_scc1 .LBB0_590
	s_cmp_ge_u32 s51, s48
	s_cbranch_scc1 .LBB0_593
	s_add_u32 s12, s40, 0xffffe000
	s_addc_u32 s13, s41, -1
	s_cmp_gt_i32 s8, 2
	s_cselect_b32 s54, -3, 2
	s_add_i32 s54, s54, s8
	s_lshl_b32 s55, s54, 13
	s_add_i32 s55, s55, s46
	s_mov_b32 m0, s55
	s_xor_b32 s55, s55, 0x1000
	global_load_lds_dwordx4 v134, s[12:13]
	s_mov_b32 m0, s55
	s_nop 0
	global_load_lds_dwordx4 v189, s[12:13]
	s_add_u32 s12, s6, 0xffffe000
	s_addc_u32 s13, s7, -1
	s_lshl_b32 s54, s54, 14
	s_add_i32 s54, s54, s47
	s_mov_b32 m0, s54
	s_xor_b32 s54, s54, 0x1000
	global_load_lds_dwordx4 v134, s[12:13]
	s_mov_b32 m0, s54
	s_nop 0
	global_load_lds_dwordx4 v189, s[12:13]
.LBB0_593:
	s_cmp_ge_u32 s49, s48
	s_cbranch_scc1 .LBB0_590
	s_cmp_gt_i32 s8, 1
	s_cselect_b32 s12, -2, 3
	s_add_i32 s12, s12, s8
	s_lshl_b32 s13, s12, 13
	s_add_i32 s13, s13, s46
	s_mov_b32 m0, s13
	s_xor_b32 s13, s13, 0x1000
	global_load_lds_dwordx4 v134, s[40:41]
	s_mov_b32 m0, s13
	s_nop 0
	global_load_lds_dwordx4 v189, s[40:41]
	s_lshl_b32 s12, s12, 14
	s_add_i32 s12, s12, s47
	s_mov_b32 m0, s12
	s_xor_b32 s12, s12, 0x1000
	global_load_lds_dwordx4 v134, s[6:7]
	s_mov_b32 m0, s12
	s_nop 0
	global_load_lds_dwordx4 v189, s[6:7]
	s_branch .LBB0_590
